# ssd3 item-start C-row staging loads batched; barrier first-use poll loads in flight
# speedup vs baseline: 1.0014x; 1.0014x over previous
.LBB0_35:
	s_and_b32 s4, s29, 7
	v_lshl_or_b32 v162, s4, 2, v151
	v_or_b32_e32 v2, v162, v142
	v_readlane_b32 s8, v251, 2
	v_ashrrev_i32_e32 v3, 31, v2
	v_readlane_b32 s10, v251, 4
	v_readlane_b32 s11, v251, 5
	s_barrier
	s_nop 0
	v_lshl_add_u64 v[2:3], v[2:3], 2, s[10:11]
	global_load_dword v3, v[2:3], off
	s_ashr_i32 s24, s29, 10
	s_bfe_u32 s2, s29, 0x60004
	s_ashr_i32 s25, s24, 31
	s_mul_i32 s1, s24, 0x4100
	s_lshl_b32 s50, s2, 8
	s_mul_hi_i32 s0, s24, 0x4100
	s_add_u32 s1, s1, s50
	s_addc_u32 s0, s0, 0
	s_add_u32 s6, s1, 0x100
	s_addc_u32 s67, s0, 0
	s_mov_b32 s0, 0x3fb8aa3b
	v_mov_b32_e32 v7, s67
	v_or_b32_e32 v6, s6, v152
	v_lshlrev_b64 v[6:7], 8, v[6:7]
	v_mov_b32_e32 v13, s67
	v_or_b32_e32 v12, s6, v156
	v_lshlrev_b64 v[12:13], 8, v[12:13]
	s_bfe_u32 s35, s29, 0x10003
	s_mov_b32 s7, s67
	s_lshl_b32 s8, s35, 7
	s_movk_i32 s3, 0x110
	v_lshl_add_u32 v189, s35, 9, v171
	s_mov_b32 s5, 0
	v_readlane_b32 s9, v251, 3
	v_readlane_b32 s12, v251, 6
	v_readlane_b32 s13, v251, 7
	v_readlane_b32 s14, v251, 8
	v_readlane_b32 s15, v251, 9
	v_readlane_b32 s16, v251, 10
	v_readlane_b32 s17, v251, 11
	v_readlane_b32 s18, v251, 12
	v_readlane_b32 s19, v251, 13
	v_readlane_b32 s20, v251, 14
	v_readlane_b32 s21, v251, 15
	v_readlane_b32 s22, v251, 16
	v_readlane_b32 s23, v251, 17
	s_waitcnt vmcnt(0)
	v_mul_f32_e32 v2, 0x3fb8aa3b, v3
	v_fma_f32 v4, v3, s0, -v2
	v_rndne_f32_e32 v5, v2
	v_fmac_f32_e32 v4, 0x32a5705f, v3
	v_sub_f32_e32 v2, v2, v5
	v_add_f32_e32 v2, v2, v4
	v_exp_f32_e32 v2, v2
	v_cvt_i32_f32_e32 v4, v5
	s_mov_b32 s0, 0xc2ce8ed0
	v_cmp_ngt_f32_e32 vcc, s0, v3
	s_mov_b32 s0, 0x42b17218
	v_ldexp_f32 v4, v2, v4
	v_cndmask_b32_e32 v4, 0, v4, vcc
	v_cmp_nlt_f32_e32 vcc, s0, v3
	v_mov_b32_e32 v5, v1
	v_readlane_b32 s0, v254, 9
	v_cndmask_b32_e32 v10, v219, v4, vcc
	v_lshlrev_b32_e32 v4, 2, v162
	v_lshl_add_u64 v[8:9], v[146:147], 0, v[4:5]
	v_mov_b32_e32 v5, s67
	v_or_b32_e32 v4, s6, v144
	v_lshlrev_b64 v[4:5], 8, v[4:5]
	v_lshl_add_u64 v[4:5], v[8:9], 0, v[4:5]
	v_lshl_add_u64 v[6:7], v[8:9], 0, v[6:7]
	global_load_dword v4, v[4:5], off
	v_readlane_b32 s1, v254, 10
	global_load_dword v5, v[6:7], off
	v_mov_b32_e32 v7, s67
	v_or_b32_e32 v6, s6, v154
	v_lshlrev_b64 v[6:7], 8, v[6:7]
	v_lshl_add_u64 v[6:7], v[8:9], 0, v[6:7]
	v_lshl_add_u64 v[8:9], v[8:9], 0, v[12:13]
	global_load_dword v6, v[6:7], off
	v_mov_b32_e32 v2, 0
	global_load_dword v7, v[8:9], off
	v_mov_b32_e32 v34, v2
	v_mov_b32_e32 v35, v2
	v_mov_b32_e32 v36, v2
	v_mov_b32_e32 v37, v2
	v_mov_b32_e32 v38, v2
	v_mov_b32_e32 v39, v2
	v_mov_b32_e32 v40, v2
	v_mov_b32_e32 v41, v2
	v_mov_b32_e32 v42, v2
	v_mov_b32_e32 v43, v2
	v_mov_b32_e32 v44, v2
	v_mov_b32_e32 v45, v2
	v_mov_b32_e32 v46, v2
	v_mov_b32_e32 v47, v2
	v_mov_b32_e32 v48, v2
	v_mov_b32_e32 v49, v2
	v_mov_b32_e32 v18, v2
	v_mov_b32_e32 v19, v2
	v_mov_b32_e32 v20, v2
	v_mov_b32_e32 v21, v2
	v_mov_b32_e32 v22, v2
	v_mov_b32_e32 v23, v2
	v_mov_b32_e32 v24, v2
	v_mov_b32_e32 v25, v2
	v_mov_b32_e32 v26, v2
	v_mov_b32_e32 v27, v2
	v_mov_b32_e32 v28, v2
	v_mov_b32_e32 v29, v2
	v_mov_b32_e32 v30, v2
	v_mov_b32_e32 v31, v2
	v_mov_b32_e32 v32, v2
	v_mov_b32_e32 v33, v2
	v_mov_b32_e32 v50, v2
	v_mov_b32_e32 v51, v2
	v_mov_b32_e32 v52, v2
	v_mov_b32_e32 v53, v2
	v_mov_b32_e32 v54, v2
	v_mov_b32_e32 v55, v2
	v_mov_b32_e32 v56, v2
	v_mov_b32_e32 v57, v2
	v_mov_b32_e32 v58, v2
	v_mov_b32_e32 v59, v2
	v_mov_b32_e32 v60, v2
	v_mov_b32_e32 v61, v2
	v_mov_b32_e32 v62, v2
	v_mov_b32_e32 v63, v2
	v_mov_b32_e32 v64, v2
	v_mov_b32_e32 v65, v2
	s_waitcnt vmcnt(2)
	v_pk_mul_f32 v[8:9], v[4:5], v[10:11] op_sel_hi:[1,0] neg_lo:[0,1] neg_hi:[0,1]
	s_nop 0
	v_pk_fma_f32 v[12:13], v[4:5], v[10:11], v[8:9] op_sel:[0,0,1] op_sel_hi:[1,0,0] neg_lo:[0,1,0] neg_hi:[0,1,0]
	s_waitcnt vmcnt(0)
	v_mul_f32_e64 v14, v7, -v10
	v_mov_b32_e32 v9, v12
	v_pk_fma_f32 v[12:13], v[6:7], v[10:11], v[12:13] op_sel_hi:[1,0,1] neg_lo:[0,1,0] neg_hi:[0,1,0]
	s_nop 0
	v_pk_add_f32 v[14:15], v[12:13], v[14:15] op_sel_hi:[1,0]
	ds_bpermute_b32 v3, v143, v14
	v_mov_b32_e32 v13, v14
	s_waitcnt lgkmcnt(0)
	v_add_f32_e32 v3, v14, v3
	v_cndmask_b32_e64 v3, v3, v14, s[0:1]
	ds_bpermute_b32 v11, v153, v3
	v_readlane_b32 s0, v254, 11
	v_readlane_b32 s1, v254, 12
	s_waitcnt lgkmcnt(0)
	v_add_f32_e32 v11, v3, v11
	v_cndmask_b32_e64 v3, v11, v3, s[0:1]
	ds_bpermute_b32 v11, v155, v3
	v_readlane_b32 s0, v254, 13
	v_readlane_b32 s1, v254, 14
	s_waitcnt lgkmcnt(0)
	v_add_f32_e32 v11, v3, v11
	v_cndmask_b32_e64 v3, v11, v3, s[0:1]
	ds_bpermute_b32 v11, v157, v3
	v_readlane_b32 s0, v254, 15
	v_readlane_b32 s1, v254, 16
	s_waitcnt lgkmcnt(0)
	v_add_f32_e32 v11, v3, v11
	v_cndmask_b32_e64 v3, v11, v3, s[0:1]
	ds_bpermute_b32 v11, v163, v3
	v_readlane_b32 s0, v254, 17
	v_readlane_b32 s1, v254, 18
	s_waitcnt lgkmcnt(0)
	v_add_f32_e32 v11, v3, v11
	v_cndmask_b32_e64 v3, v11, v3, s[0:1]
	ds_bpermute_b32 v11, v166, v3
	v_readlane_b32 s0, v254, 19
	v_readlane_b32 s1, v254, 20
	s_waitcnt lgkmcnt(0)
	v_add_f32_e32 v11, v3, v11
	v_cndmask_b32_e64 v3, v11, v3, s[0:1]
	v_sub_f32_e32 v16, v3, v14
	ds_bpermute_b32 v14, v167, v3
	v_pk_add_f32 v[8:9], v[8:9], v[16:17] op_sel_hi:[1,0]
	v_pk_add_f32 v[12:13], v[12:13], v[16:17] op_sel_hi:[1,0]
	v_readlane_b32 s0, v255, 10
	v_readlane_b32 s1, v255, 11
	s_waitcnt lgkmcnt(0)
	v_pk_add_f32 v[16:17], v[14:15], v[8:9] op_sel_hi:[0,1] neg_lo:[0,1] neg_hi:[0,1]
	v_pk_add_f32 v[14:15], v[14:15], v[12:13] op_sel_hi:[0,1] neg_lo:[0,1] neg_hi:[0,1]
	v_pk_fma_f32 v[16:17], v[4:5], v[10:11], v[16:17] op_sel_hi:[1,0,1] neg_lo:[0,1,0] neg_hi:[0,1,0]
	v_pk_fma_f32 v[10:11], v[6:7], v[10:11], v[14:15] op_sel_hi:[1,0,1] neg_lo:[0,1,0] neg_hi:[0,1,0]
	v_cndmask_b32_e64 v9, v17, v9, s[0:1]
	v_cndmask_b32_e64 v8, v16, v8, s[0:1]
	v_cndmask_b32_e64 v11, v11, v13, s[0:1]
	v_cndmask_b32_e64 v10, v10, v12, s[0:1]
	v_writelane_b32 v255, s6, 8
	s_or_b32 s66, s6, s8
	v_mov_b32_e32 v3, v179
	s_lshl_b32 s0, s4, 8
	ds_write_b128 v176, v[8:11]
	ds_write_b128 v177, v[4:7]
	s_add_u32 s0, s38, s0
	v_lshlrev_b32_e32 v4, 4, v3
	v_ashrrev_i32_e32 v12, 4, v3
	s_addc_u32 s1, s39, 0
	v_and_b32_e32 v4, 0xf0, v4
	v_mov_b32_e32 v5, v1
	v_ashrrev_i32_e32 v13, 31, v12
	v_writelane_b32 v255, s7, 9
	v_lshl_add_u64 v[6:7], s[0:1], 0, v[4:5]
	s_mov_b64 s[6:7], 0x1800
	v_add_u32_e32 v10, 32, v4
	v_lshl_add_u64 v[4:5], s[66:67], 0, v[12:13]
	v_lshl_add_u64 v[8:9], v[6:7], 0, s[6:7]
	v_lshlrev_b64 v[4:5], 13, v[4:5]
	v_lshl_add_u64 v[4:5], v[8:9], 0, v[4:5]
	global_load_dwordx4 v[200:203], v[4:5], off
	v_mad_u64_u32 v[12:13], s[6:7], v12, s3, v[10:11]
	v_mov_b32_e32 v222, v12
	s_lshl_b32 s2, s2, 19
	v_mov_b32_e32 v14, v2
	v_mov_b32_e32 v15, v2
	v_mov_b32_e32 v16, v2
	v_mov_b32_e32 v17, v2
	v_add_u32_e32 v4, 0x200, v3
	v_ashrrev_i32_e32 v12, 4, v4
	v_ashrrev_i32_e32 v13, 31, v12
	v_lshl_add_u64 v[4:5], s[66:67], 0, v[12:13]
	v_lshlrev_b64 v[4:5], 13, v[4:5]
	v_lshl_add_u64 v[4:5], v[8:9], 0, v[4:5]
	global_load_dwordx4 v[204:207], v[4:5], off
	v_mad_u64_u32 v[12:13], s[6:7], v12, s3, v[10:11]
	v_mov_b32_e32 v223, v12
	v_add_u32_e32 v4, 0x400, v3
	v_ashrrev_i32_e32 v12, 4, v4
	v_ashrrev_i32_e32 v13, 31, v12
	v_lshl_add_u64 v[4:5], s[66:67], 0, v[12:13]
	v_lshlrev_b64 v[4:5], 13, v[4:5]
	v_lshl_add_u64 v[4:5], v[8:9], 0, v[4:5]
	global_load_dwordx4 v[208:211], v[4:5], off
	v_mad_u64_u32 v[12:13], s[6:7], v12, s3, v[10:11]
	v_mov_b32_e32 v224, v12
	v_add_u32_e32 v3, 0x600, v3
	v_ashrrev_i32_e32 v12, 4, v3
	v_ashrrev_i32_e32 v13, 31, v12
	v_lshl_add_u64 v[4:5], s[66:67], 0, v[12:13]
	v_lshlrev_b64 v[4:5], 13, v[4:5]
	v_lshl_add_u64 v[4:5], v[8:9], 0, v[4:5]
	global_load_dwordx4 v[212:215], v[4:5], off
	v_mad_u64_u32 v[8:9], s[6:7], v12, s3, v[10:11]
	s_mov_b32 s3, s51
	v_mov_b32_e32 v3, v2
	v_mov_b32_e32 v9, v2
	v_mov_b32_e32 v10, v2
	v_mov_b32_e32 v11, v2
	v_mov_b32_e32 v12, v2
	v_mov_b32_e32 v13, v2
	s_waitcnt vmcnt(3)
	ds_write_b128 v222, v[200:203]
	s_waitcnt vmcnt(2)
	ds_write_b128 v223, v[204:207]
	s_waitcnt vmcnt(1)
	ds_write_b128 v224, v[208:211]
	s_waitcnt vmcnt(0)
	ds_write_b128 v8, v[212:215]
	v_lshlrev_b32_e32 v4, 14, v162
	v_mov_b32_e32 v5, v1
	v_lshl_add_u64 v[6:7], v[148:149], 0, s[2:3]
	v_lshl_add_u64 v[164:165], v[6:7], 0, v[4:5]
	s_mov_b64 s[2:3], -1
	v_mov_b32_e32 v4, v2
	v_mov_b32_e32 v5, v2
	v_mov_b32_e32 v6, v2
	v_mov_b32_e32 v7, v2
	v_mov_b32_e32 v8, v2
	s_waitcnt lgkmcnt(0)
	s_barrier
